# M2 item loop waits only for prefetch loads (vmcnt(4)), row-pass gpost waits count the interleaved stores (vmcnt(3))
# baseline (speedup 1.0000x reference)
.LBB0_555:
	s_and_b32 s0, s4, 7
	s_lshl_b32 s1, s0, 2
	v_readlane_b32 s4, v255, 37
	v_mov_b32_e32 v60, s1
	v_readlane_b32 s5, v255, 38
	v_ashrrev_i32_e32 v155, 31, v154
	s_nop 3
	global_load_dword v116, v60, s[4:5]
	global_load_dword v117, v60, s[4:5] offset:32
	v_readlane_b32 s4, v252, 22
	v_ashrrev_i32_e32 v177, 4, v2
	v_lshlrev_b64 v[0:1], 11, v[154:155]
	v_readlane_b32 s5, v252, 23
	s_lshl_b32 s18, s0, 8
	v_lshlrev_b32_e32 v172, 2, v177
	v_lshl_add_u64 v[0:1], s[4:5], 0, v[0:1]
	v_lshl_add_u64 v[0:1], v[0:1], 0, s[18:19]
	v_ashrrev_i32_e32 v173, 31, v172
	v_lshl_add_u64 v[0:1], v[172:173], 1, v[0:1]
	global_load_dwordx2 v[162:163], v[0:1], off
	global_load_dwordx2 v[160:161], v[0:1], off offset:32
	global_load_dwordx2 v[158:159], v[0:1], off offset:64
	global_load_dwordx2 v[156:157], v[0:1], off offset:96
	global_load_dwordx2 v[152:153], v[0:1], off offset:128
	global_load_dwordx2 v[150:151], v[0:1], off offset:160
	global_load_dwordx2 v[148:149], v[0:1], off offset:192
	s_nop 0
	global_load_dwordx2 v[0:1], v[0:1], off offset:224
	v_mul_u32_u24_e32 v62, 0xa0, v175
	v_and_b32_e32 v155, -16, v2
	v_add_u32_e32 v60, 1, v180
	v_sub_u32_e32 v61, 0x80, v180
	v_add3_u32 v136, 0, v62, v155
	v_cvt_f32_i32_e32 v124, v60
	v_cvt_f32_i32_e32 v125, v61
	ds_read_b128 v[60:63], v136 offset:26624
	ds_read_b128 v[64:67], v136 offset:26688
	ds_read_b128 v[68:71], v136 offset:47104
	ds_read_b128 v[72:75], v136 offset:47168
	ds_read_b128 v[76:79], v136 offset:29184
	ds_read_b128 v[80:83], v136 offset:29248
	ds_read_b128 v[84:87], v136 offset:49664
	ds_read_b128 v[88:91], v136 offset:49728
	ds_read_b128 v[92:95], v136 offset:31744
	ds_read_b128 v[96:99], v136 offset:31808
	ds_read_b128 v[100:103], v136 offset:52224
	ds_read_b128 v[104:107], v136 offset:52288
	ds_read_b128 v[108:111], v136 offset:34304
	ds_read_b128 v[112:115], v136 offset:34368
	s_waitcnt vmcnt(9)
	v_mul_f32_e32 v116, 0x3fb8aa3b, v116
	s_waitcnt vmcnt(8)
	v_mul_f32_e32 v117, 0x3fb8aa3b, v117
	v_exp_f32_e32 v173, v116
	v_exp_f32_e32 v176, v117
	ds_read_b128 v[116:119], v136 offset:54784
	ds_read_b128 v[120:123], v136 offset:54848
	v_mul_f32_e64 v124, v124, -v173
	v_mul_f32_e64 v125, v125, -v176
	v_mul_f32_e32 v124, 0x3fb8aa3b, v124
	v_mul_f32_e32 v125, 0x3fb8aa3b, v125
	v_exp_f32_e32 v140, v124
	v_exp_f32_e32 v142, v125
	s_waitcnt lgkmcnt(14)
	v_mfma_f32_16x16x32_bf16 v[60:63], v[60:63], v[56:59], 0
	v_mfma_f32_16x16x32_bf16 v[60:63], v[64:67], v[52:55], v[60:63]
	s_waitcnt lgkmcnt(13)
	v_mfma_f32_16x16x32_bf16 v[64:67], v[68:71], v[56:59], 0
	s_waitcnt lgkmcnt(12)
	v_mfma_f32_16x16x32_bf16 v[64:67], v[72:75], v[52:55], v[64:67]
	s_waitcnt lgkmcnt(9)
	v_mfma_f32_16x16x32_bf16 v[72:75], v[84:87], v[56:59], 0
	v_mfma_f32_16x16x32_bf16 v[68:71], v[76:79], v[56:59], 0
	s_nop 4
	v_mul_f32_e64 v64, v142, v64
	v_mul_f32_e64 v65, v142, v65
	v_pk_mul_f32 v[66:67], v[142:143], v[66:67] op_sel_hi:[0,1]
	v_pk_fma_f32 v[60:61], v[140:141], v[60:61], v[64:65] op_sel_hi:[0,1,1]
	s_waitcnt lgkmcnt(8)
	v_mfma_f32_16x16x32_bf16 v[72:75], v[88:91], v[52:55], v[72:75]
	v_fma_f32 v62, v140, v62, v66
	v_fma_f32 v63, v140, v63, v67
	v_mfma_f32_16x16x32_bf16 v[68:71], v[80:83], v[52:55], v[68:71]
	s_waitcnt lgkmcnt(5)
	v_mfma_f32_16x16x32_bf16 v[80:83], v[100:103], v[56:59], 0
	s_nop 2
	v_mul_f32_e64 v64, v142, v74
	v_mul_f32_e64 v65, v142, v75
	v_pk_mul_f32 v[72:73], v[142:143], v[72:73] op_sel_hi:[0,1]
	v_pk_fma_f32 v[66:67], v[140:141], v[70:71], v[64:65] op_sel_hi:[0,1,1]
	v_mfma_f32_16x16x32_bf16 v[76:79], v[92:95], v[56:59], 0
	v_fma_f32 v64, v140, v68, v72
	v_fma_f32 v65, v140, v69, v73
	s_waitcnt lgkmcnt(1)
	v_mfma_f32_16x16x32_bf16 v[72:75], v[116:119], v[56:59], 0
	v_mfma_f32_16x16x32_bf16 v[80:83], v[104:107], v[52:55], v[80:83]
	v_mfma_f32_16x16x32_bf16 v[76:79], v[96:99], v[52:55], v[76:79]
	v_mfma_f32_16x16x32_bf16 v[84:87], v[108:111], v[56:59], 0
	s_nop 5
	v_mul_f32_e64 v68, v142, v82
	v_mul_f32_e64 v69, v142, v83
	v_pk_mul_f32 v[80:81], v[142:143], v[80:81] op_sel_hi:[0,1]
	v_pk_fma_f32 v[70:71], v[140:141], v[78:79], v[68:69] op_sel_hi:[0,1,1]
	s_waitcnt lgkmcnt(0)
	v_mfma_f32_16x16x32_bf16 v[72:75], v[120:123], v[52:55], v[72:75]
	v_fma_f32 v68, v140, v76, v80
	v_fma_f32 v69, v140, v77, v81
	s_nop 5
	v_pk_mul_f32 v[76:77], v[142:143], v[74:75] op_sel_hi:[0,1]
	v_pk_mul_f32 v[78:79], v[142:143], v[72:73] op_sel_hi:[0,1]
	v_mfma_f32_16x16x32_bf16 v[72:75], v[112:115], v[52:55], v[84:87]
	s_nop 7
	v_pk_fma_f32 v[74:75], v[140:141], v[74:75], v[76:77] op_sel_hi:[0,1,1]
	v_pk_fma_f32 v[72:73], v[140:141], v[72:73], v[78:79] op_sel_hi:[0,1,1]
	ds_read_b128 v[76:79], v136 offset:36864
	ds_read_b128 v[80:83], v136 offset:36928
	ds_read_b128 v[84:87], v136 offset:57344
	ds_read_b128 v[88:91], v136 offset:57408
	ds_read_b128 v[92:95], v136 offset:39424
	ds_read_b128 v[96:99], v136 offset:39488
	ds_read_b128 v[100:103], v136 offset:59904
	ds_read_b128 v[104:107], v136 offset:59968
	ds_read_b128 v[108:111], v136 offset:41984
	ds_read_b128 v[112:115], v136 offset:42048
	ds_read_b128 v[116:119], v136 offset:62464
	ds_read_b128 v[120:123], v136 offset:62528
	ds_read_b128 v[124:127], v136 offset:44544
	ds_read_b128 v[128:131], v136 offset:44608
	ds_read_b128 v[132:135], v136 offset:65024
	ds_read_b128 v[136:139], v136 offset:65088
	s_waitcnt lgkmcnt(14)
	v_mfma_f32_16x16x32_bf16 v[76:79], v[76:79], v[56:59], 0
	v_mfma_f32_16x16x32_bf16 v[76:79], v[80:83], v[52:55], v[76:79]
	s_waitcnt lgkmcnt(13)
	v_mfma_f32_16x16x32_bf16 v[80:83], v[84:87], v[56:59], 0
	s_waitcnt lgkmcnt(12)
	v_mfma_f32_16x16x32_bf16 v[80:83], v[88:91], v[52:55], v[80:83]
	s_waitcnt lgkmcnt(9)
	v_mfma_f32_16x16x32_bf16 v[88:91], v[100:103], v[56:59], 0
	v_mfma_f32_16x16x32_bf16 v[84:87], v[92:95], v[56:59], 0
	s_nop 4
	v_mul_f32_e64 v80, v142, v80
	v_mul_f32_e64 v81, v142, v81
	v_pk_mul_f32 v[82:83], v[142:143], v[82:83] op_sel_hi:[0,1]
	v_pk_fma_f32 v[76:77], v[140:141], v[76:77], v[80:81] op_sel_hi:[0,1,1]
	s_waitcnt lgkmcnt(8)
	v_mfma_f32_16x16x32_bf16 v[88:91], v[104:107], v[52:55], v[88:91]
	v_fma_f32 v78, v140, v78, v82
	v_fma_f32 v79, v140, v79, v83
	v_mfma_f32_16x16x32_bf16 v[84:87], v[96:99], v[52:55], v[84:87]
	s_waitcnt lgkmcnt(5)
	v_mfma_f32_16x16x32_bf16 v[96:99], v[116:119], v[56:59], 0
	s_nop 2
	v_mul_f32_e64 v80, v142, v90
	v_mul_f32_e64 v81, v142, v91
	v_pk_mul_f32 v[88:89], v[142:143], v[88:89] op_sel_hi:[0,1]
	v_pk_fma_f32 v[82:83], v[140:141], v[86:87], v[80:81] op_sel_hi:[0,1,1]
	v_mfma_f32_16x16x32_bf16 v[92:95], v[108:111], v[56:59], 0
	v_fma_f32 v80, v140, v84, v88
	v_fma_f32 v81, v140, v85, v89
	s_waitcnt lgkmcnt(1)
	v_mfma_f32_16x16x32_bf16 v[88:91], v[132:135], v[56:59], 0
	v_mfma_f32_16x16x32_bf16 v[96:99], v[120:123], v[52:55], v[96:99]
	v_mfma_f32_16x16x32_bf16 v[92:95], v[112:115], v[52:55], v[92:95]
	v_mfma_f32_16x16x32_bf16 v[100:103], v[124:127], v[56:59], 0
	s_nop 5
	v_mul_f32_e64 v84, v142, v98
	v_mul_f32_e64 v85, v142, v99
	v_pk_mul_f32 v[96:97], v[142:143], v[96:97] op_sel_hi:[0,1]
	v_pk_fma_f32 v[86:87], v[140:141], v[94:95], v[84:85] op_sel_hi:[0,1,1]
	s_waitcnt lgkmcnt(0)
	v_mfma_f32_16x16x32_bf16 v[88:91], v[136:139], v[52:55], v[88:91]
	v_fma_f32 v84, v140, v92, v96
	v_fma_f32 v85, v140, v93, v97
	s_nop 5
	v_pk_mul_f32 v[92:93], v[142:143], v[90:91] op_sel_hi:[0,1]
	v_pk_mul_f32 v[94:95], v[142:143], v[88:89] op_sel_hi:[0,1]
	v_mfma_f32_16x16x32_bf16 v[88:91], v[128:131], v[52:55], v[100:103]
	s_nop 7
	v_pk_fma_f32 v[90:91], v[140:141], v[90:91], v[92:93] op_sel_hi:[0,1,1]
	v_pk_fma_f32 v[88:89], v[140:141], v[88:89], v[94:95] op_sel_hi:[0,1,1]
	v_lshlrev_b32_e32 v93, 1, v2
	v_lshlrev_b32_e32 v92, 1, v175
	v_and_b32_e32 v93, 6, v93
	v_and_or_b32 v92, v92, 24, v93
	v_mul_u32_u24_e32 v92, 0xd0, v92
	v_add3_u32 v96, 0, v92, v155
	ds_read_b128 v[92:95], v96
	ds_read_b128 v[144:147], v96 offset:64
	ds_read_b128 v[182:185], v96 offset:208
	ds_read_b128 v[186:189], v96 offset:272
	ds_read_b128 v[140:143], v96 offset:6656
	ds_read_b128 v[136:139], v96 offset:6720
	ds_read_b128 v[132:135], v96 offset:6864
	ds_read_b128 v[112:115], v96 offset:6928
	ds_read_b128 v[128:131], v96 offset:13312
	ds_read_b128 v[124:127], v96 offset:13376
	ds_read_b128 v[120:123], v96 offset:13520
	ds_read_b128 v[116:119], v96 offset:13584
	ds_read_b128 v[108:111], v96 offset:19968
	ds_read_b128 v[104:107], v96 offset:20032
	ds_read_b128 v[100:103], v96 offset:20176
	ds_read_b128 v[96:99], v96 offset:20240
	v_lshlrev_b32_e32 v178, 3, v177
	v_sub_u32_e32 v179, v180, v178
	v_sub_u32_e32 v169, 0, v179
	v_max_i32_e32 v169, v179, v169
	v_cvt_f32_u32_e32 v169, v169
	v_cmp_gt_i32_e32 vcc, 0, v179
	v_add_u32_e32 v168, -1, v179
	s_waitcnt lgkmcnt(14)
	v_mfma_f32_16x16x32_bf16 v[92:95], v[92:95], v[56:59], 0
	v_cndmask_b32_e32 v181, v173, v176, vcc
	v_mul_f32_e64 v169, -v181, v169
	v_cmp_lt_i32_e32 vcc, 0, v179
	v_sub_u32_e32 v181, 1, v179
	v_mfma_f32_16x16x32_bf16 v[92:95], v[144:147], v[52:55], v[92:95]
	v_cndmask_b32_e32 v168, v181, v168, vcc
	v_cvt_f32_u32_e32 v168, v168
	v_cndmask_b32_e32 v181, v176, v173, vcc
	s_waitcnt lgkmcnt(13)
	v_mfma_f32_16x16x32_bf16 v[144:147], v[182:185], v[56:59], 0
	v_mul_f32_e32 v169, 0x3fb8aa3b, v169
	v_mul_f32_e64 v168, -v181, v168
	v_mul_f32_e32 v168, 0x3fb8aa3b, v168
	v_exp_f32_e32 v168, v168
	s_waitcnt lgkmcnt(12)
	v_mfma_f32_16x16x32_bf16 v[144:147], v[186:189], v[52:55], v[144:147]
	v_exp_f32_e32 v169, v169
	v_or_b32_e32 v181, 1, v178
	s_movk_i32 s22, 0x70
	v_cmp_gt_i32_e64 s[0:1], s22, v181
	v_cmp_gt_i32_e32 vcc, 14, v177
	s_and_b64 s[0:1], s[2:3], s[0:1]
	s_and_b64 s[4:5], s[2:3], vcc
	v_cndmask_b32_e64 v168, v168, 0, s[0:1]
	v_cndmask_b32_e64 v169, v169, 0, s[4:5]
	v_mul_f32_e32 v144, v168, v144
	v_or_b32_e32 v168, 2, v178
	v_mul_f32_e32 v92, v169, v92
	v_sub_u32_e32 v169, v180, v168
	v_sub_u32_e32 v182, 0, v169
	v_cmp_gt_i32_e32 vcc, 0, v169
	v_add_u32_e32 v181, -1, v169
	v_max_i32_e32 v182, v169, v182
	v_cndmask_b32_e32 v183, v173, v176, vcc
	v_cmp_lt_i32_e32 vcc, 0, v169
	v_sub_u32_e32 v169, 1, v169
	v_cvt_f32_u32_e32 v182, v182
	v_cndmask_b32_e32 v169, v169, v181, vcc
	v_cvt_f32_u32_e32 v169, v169
	v_cndmask_b32_e32 v181, v176, v173, vcc
	v_mul_f32_e64 v182, -v183, v182
	v_mul_f32_e32 v182, 0x3fb8aa3b, v182
	v_mul_f32_e64 v169, -v181, v169
	v_exp_f32_e32 v182, v182
	v_mul_f32_e32 v169, 0x3fb8aa3b, v169
	v_exp_f32_e32 v169, v169
	v_cmp_gt_i32_e32 vcc, s22, v168
	v_or_b32_e32 v168, 3, v178
	v_cmp_gt_i32_e64 s[0:1], s22, v168
	s_and_b64 s[4:5], s[2:3], vcc
	v_cndmask_b32_e64 v168, v182, 0, s[4:5]
	s_and_b64 s[0:1], s[2:3], s[0:1]
	v_cndmask_b32_e64 v169, v169, 0, s[0:1]
	v_mul_f32_e32 v93, v168, v93
	v_or_b32_e32 v168, 4, v178
	v_mul_f32_e32 v145, v169, v145
	v_sub_u32_e32 v169, v180, v168
	v_sub_u32_e32 v182, 0, v169
	v_cmp_gt_i32_e32 vcc, 0, v169
	v_add_u32_e32 v181, -1, v169
	v_max_i32_e32 v182, v169, v182
	v_cndmask_b32_e32 v183, v173, v176, vcc
	v_cmp_lt_i32_e32 vcc, 0, v169
	v_sub_u32_e32 v169, 1, v169
	v_cvt_f32_u32_e32 v182, v182
	v_cndmask_b32_e32 v169, v169, v181, vcc
	v_cvt_f32_u32_e32 v169, v169
	v_cndmask_b32_e32 v181, v176, v173, vcc
	v_mul_f32_e64 v182, -v183, v182
	v_mul_f32_e32 v182, 0x3fb8aa3b, v182
	v_mul_f32_e64 v169, -v181, v169
	v_exp_f32_e32 v182, v182
	v_mul_f32_e32 v169, 0x3fb8aa3b, v169
	v_exp_f32_e32 v169, v169
	v_cmp_gt_i32_e32 vcc, s22, v168
	v_or_b32_e32 v168, 5, v178
	v_cmp_gt_i32_e64 s[0:1], s22, v168
	s_and_b64 s[4:5], s[2:3], vcc
	v_cndmask_b32_e64 v168, v182, 0, s[4:5]
	s_and_b64 s[0:1], s[2:3], s[0:1]
	v_cndmask_b32_e64 v169, v169, 0, s[0:1]
	v_mul_f32_e32 v94, v168, v94
	v_or_b32_e32 v168, 6, v178
	s_waitcnt lgkmcnt(9)
	v_mfma_f32_16x16x32_bf16 v[132:135], v[132:135], v[56:59], 0
	v_mul_f32_e32 v146, v169, v146
	v_sub_u32_e32 v169, v180, v168
	v_sub_u32_e32 v181, 0, v169
	v_cmp_gt_i32_e32 vcc, 0, v169
	v_add_u32_e32 v180, -1, v169
	v_max_i32_e32 v181, v169, v181
	v_cndmask_b32_e32 v182, v173, v176, vcc
	v_cmp_lt_i32_e32 vcc, 0, v169
	v_sub_u32_e32 v169, 1, v169
	s_waitcnt lgkmcnt(8)
	v_mfma_f32_16x16x32_bf16 v[112:115], v[112:115], v[52:55], v[132:135]
	v_cndmask_b32_e32 v169, v169, v180, vcc
	v_cndmask_b32_e32 v180, v176, v173, vcc
	v_cmp_gt_i32_e32 vcc, s22, v168
	v_subrev_u32_e32 v132, 32, v179
	s_and_b64 s[4:5], s[2:3], vcc
	v_sub_u32_e32 v134, 32, v179
	v_cmp_gt_i32_e32 vcc, 0, v132
	v_cvt_f32_u32_e32 v169, v169
	v_subrev_u32_e32 v133, 33, v179
	v_max_i32_e32 v134, v132, v134
	v_cndmask_b32_e32 v135, v173, v176, vcc
	v_cmp_lt_i32_e32 vcc, 0, v132
	v_sub_u32_e32 v132, 33, v179
	v_cvt_f32_u32_e32 v181, v181
	v_cndmask_b32_e32 v132, v132, v133, vcc
	v_cvt_f32_u32_e32 v132, v132
	v_mul_f32_e64 v169, -v180, v169
	v_cvt_f32_u32_e32 v134, v134
	v_mul_f32_e32 v169, 0x3fb8aa3b, v169
	v_cndmask_b32_e32 v133, v176, v173, vcc
	v_exp_f32_e32 v169, v169
	v_mul_f32_e64 v132, -v133, v132
	v_mul_f32_e64 v181, -v182, v181
	v_or_b32_e32 v168, 7, v178
	v_mfma_f32_16x16x32_bf16 v[140:143], v[140:143], v[56:59], 0
	v_mul_f32_e32 v132, 0x3fb8aa3b, v132
	v_mul_f32_e32 v181, 0x3fb8aa3b, v181
	v_cmp_gt_i32_e64 s[0:1], s22, v168
	v_mul_f32_e64 v134, -v135, v134
	v_exp_f32_e32 v132, v132
	v_exp_f32_e32 v181, v181
	s_and_b64 s[0:1], s[2:3], s[0:1]
	v_mul_f32_e32 v134, 0x3fb8aa3b, v134
	v_add_u32_e32 v133, 33, v178
	v_cndmask_b32_e64 v169, v169, 0, s[0:1]
	v_exp_f32_e32 v134, v134
	v_cmp_gt_i32_e64 s[0:1], s22, v133
	v_mfma_f32_16x16x32_bf16 v[136:139], v[136:139], v[52:55], v[140:143]
	s_and_b64 s[0:1], s[2:3], s[0:1]
	v_cmp_gt_i32_e32 vcc, 10, v177
	v_cndmask_b32_e64 v132, v132, 0, s[0:1]
	v_cndmask_b32_e64 v168, v181, 0, s[4:5]
	s_and_b64 s[4:5], s[2:3], vcc
	v_mul_f32_e32 v112, v132, v112
	v_subrev_u32_e32 v132, 34, v179
	v_cndmask_b32_e64 v133, v134, 0, s[4:5]
	v_sub_u32_e32 v135, 34, v179
	v_cmp_gt_i32_e32 vcc, 0, v132
	v_mul_f32_e32 v133, v133, v136
	v_subrev_u32_e32 v134, 35, v179
	v_max_i32_e32 v135, v132, v135
	v_cndmask_b32_e32 v136, v173, v176, vcc
	v_cmp_lt_i32_e32 vcc, 0, v132
	v_sub_u32_e32 v132, 35, v179
	v_cvt_f32_u32_e32 v135, v135
	v_cndmask_b32_e32 v132, v132, v134, vcc
	v_cvt_f32_u32_e32 v132, v132
	v_cndmask_b32_e32 v134, v176, v173, vcc
	v_mul_f32_e64 v135, -v136, v135
	v_mul_f32_e32 v135, 0x3fb8aa3b, v135
	v_mul_f32_e64 v132, -v134, v132
	v_mul_f32_e32 v132, 0x3fb8aa3b, v132
	v_exp_f32_e32 v132, v132
	v_add_u32_e32 v134, 35, v178
	v_exp_f32_e32 v135, v135
	v_cmp_gt_i32_e32 vcc, s22, v134
	s_and_b64 s[0:1], s[2:3], vcc
	v_cndmask_b32_e64 v132, v132, 0, s[0:1]
	v_mul_f32_e32 v113, v132, v113
	v_subrev_u32_e32 v132, 36, v179
	v_cndmask_b32_e64 v134, v135, 0, s[4:5]
	v_sub_u32_e32 v136, 36, v179
	v_cmp_gt_i32_e32 vcc, 0, v132
	v_mul_f32_e32 v134, v134, v137
	v_subrev_u32_e32 v135, 37, v179
	v_max_i32_e32 v136, v132, v136
	v_cndmask_b32_e32 v137, v173, v176, vcc
	v_cmp_lt_i32_e32 vcc, 0, v132
	v_sub_u32_e32 v132, 37, v179
	v_cvt_f32_u32_e32 v136, v136
	v_cndmask_b32_e32 v132, v132, v135, vcc
	v_cvt_f32_u32_e32 v132, v132
	v_cndmask_b32_e32 v135, v176, v173, vcc
	v_mul_f32_e64 v136, -v137, v136
	v_mul_f32_e32 v136, 0x3fb8aa3b, v136
	v_mul_f32_e64 v132, -v135, v132
	v_mul_f32_e32 v132, 0x3fb8aa3b, v132
	v_exp_f32_e32 v132, v132
	v_add_u32_e32 v135, 37, v178
	v_exp_f32_e32 v136, v136
	v_cmp_gt_i32_e32 vcc, s22, v135
	s_and_b64 s[0:1], s[2:3], vcc
	v_cndmask_b32_e64 v132, v132, 0, s[0:1]
	v_mul_f32_e32 v114, v132, v114
	v_subrev_u32_e32 v132, 38, v179
	v_cndmask_b32_e64 v135, v136, 0, s[4:5]
	v_sub_u32_e32 v137, 38, v179
	v_cmp_gt_i32_e32 vcc, 0, v132
	v_mul_f32_e32 v135, v135, v138
	v_subrev_u32_e32 v136, 39, v179
	v_max_i32_e32 v137, v132, v137
	v_cndmask_b32_e32 v138, v173, v176, vcc
	v_cmp_lt_i32_e32 vcc, 0, v132
	v_sub_u32_e32 v132, 39, v179
	s_waitcnt lgkmcnt(5)
	v_mfma_f32_16x16x32_bf16 v[120:123], v[120:123], v[56:59], 0
	v_cndmask_b32_e32 v132, v132, v136, vcc
	v_cvt_f32_u32_e32 v132, v132
	v_cndmask_b32_e32 v136, v176, v173, vcc
	s_waitcnt lgkmcnt(4)
	v_mfma_f32_16x16x32_bf16 v[116:119], v[116:119], v[52:55], v[120:123]
	v_cvt_f32_u32_e32 v137, v137
	v_mul_f32_e64 v132, -v136, v132
	v_add_u32_e32 v136, 39, v178
	v_cmp_gt_i32_e32 vcc, s22, v136
	v_subrev_u32_e32 v120, 64, v179
	s_and_b64 s[0:1], s[2:3], vcc
	v_sub_u32_e32 v122, 64, v179
	v_cmp_gt_i32_e32 vcc, 0, v120
	v_add_u32_e32 v121, 0xffffffbf, v179
	v_max_i32_e32 v122, v120, v122
	v_cndmask_b32_e32 v123, v173, v176, vcc
	v_cmp_lt_i32_e32 vcc, 0, v120
	v_sub_u32_e32 v120, 0x41, v179
	v_cvt_f32_u32_e32 v122, v122
	v_cndmask_b32_e32 v120, v120, v121, vcc
	v_cvt_f32_u32_e32 v120, v120
	v_mul_f32_e32 v132, 0x3fb8aa3b, v132
	v_cndmask_b32_e32 v121, v176, v173, vcc
	v_exp_f32_e32 v132, v132
	v_mul_f32_e64 v120, -v121, v120
	v_mul_f32_e64 v137, -v138, v137
	v_mfma_f32_16x16x32_bf16 v[128:131], v[128:131], v[56:59], 0
	v_mul_f32_e32 v120, 0x3fb8aa3b, v120
	v_mul_f32_e32 v137, 0x3fb8aa3b, v137
	v_mul_f32_e64 v122, -v123, v122
	v_exp_f32_e32 v120, v120
	v_exp_f32_e32 v137, v137
	v_mul_f32_e32 v122, 0x3fb8aa3b, v122
	v_add_u32_e32 v121, 0x41, v178
	v_cndmask_b32_e64 v132, v132, 0, s[0:1]
	v_exp_f32_e32 v122, v122
	v_cmp_gt_i32_e64 s[0:1], s22, v121
	v_mfma_f32_16x16x32_bf16 v[124:127], v[124:127], v[52:55], v[128:131]
	s_and_b64 s[0:1], s[2:3], s[0:1]
	v_cmp_gt_i32_e32 vcc, 6, v177
	v_cndmask_b32_e64 v120, v120, 0, s[0:1]
	v_cndmask_b32_e64 v136, v137, 0, s[4:5]
	s_and_b64 s[4:5], s[2:3], vcc
	v_mul_f32_e32 v116, v120, v116
	v_add_u32_e32 v120, 0xffffffbe, v179
	v_cndmask_b32_e64 v121, v122, 0, s[4:5]
	v_sub_u32_e32 v123, 0x42, v179
	v_cmp_gt_i32_e32 vcc, 0, v120
	v_mul_f32_e32 v121, v121, v124
	v_add_u32_e32 v122, 0xffffffbd, v179
	v_max_i32_e32 v123, v120, v123
	v_cndmask_b32_e32 v124, v173, v176, vcc
	v_cmp_lt_i32_e32 vcc, 0, v120
	v_sub_u32_e32 v120, 0x43, v179
	v_cvt_f32_u32_e32 v123, v123
	v_cndmask_b32_e32 v120, v120, v122, vcc
	v_cvt_f32_u32_e32 v120, v120
	v_cndmask_b32_e32 v122, v176, v173, vcc
	v_mul_f32_e64 v123, -v124, v123
	v_mul_f32_e32 v123, 0x3fb8aa3b, v123
	v_mul_f32_e64 v120, -v122, v120
	v_mul_f32_e32 v120, 0x3fb8aa3b, v120
	v_exp_f32_e32 v120, v120
	v_add_u32_e32 v122, 0x43, v178
	v_exp_f32_e32 v123, v123
	v_cmp_gt_i32_e32 vcc, s22, v122
	s_and_b64 s[0:1], s[2:3], vcc
	v_cndmask_b32_e64 v120, v120, 0, s[0:1]
	v_mul_f32_e32 v117, v120, v117
	v_add_u32_e32 v120, 0xffffffbc, v179
	v_cndmask_b32_e64 v122, v123, 0, s[4:5]
	v_sub_u32_e32 v124, 0x44, v179
	v_cmp_gt_i32_e32 vcc, 0, v120
	v_mul_f32_e32 v122, v122, v125
	v_add_u32_e32 v123, 0xffffffbb, v179
	v_max_i32_e32 v124, v120, v124
	v_cndmask_b32_e32 v125, v173, v176, vcc
	v_cmp_lt_i32_e32 vcc, 0, v120
	v_sub_u32_e32 v120, 0x45, v179
	v_cvt_f32_u32_e32 v124, v124
	v_cndmask_b32_e32 v120, v120, v123, vcc
	v_cvt_f32_u32_e32 v120, v120
	v_cndmask_b32_e32 v123, v176, v173, vcc
	v_mul_f32_e64 v124, -v125, v124
	v_mul_f32_e32 v124, 0x3fb8aa3b, v124
	v_mul_f32_e64 v120, -v123, v120
	v_mul_f32_e32 v120, 0x3fb8aa3b, v120
	v_exp_f32_e32 v120, v120
	v_add_u32_e32 v123, 0x45, v178
	v_exp_f32_e32 v124, v124
	v_cmp_gt_i32_e32 vcc, s22, v123
	s_and_b64 s[0:1], s[2:3], vcc
	v_cndmask_b32_e64 v120, v120, 0, s[0:1]
	v_mul_f32_e32 v118, v120, v118
	v_add_u32_e32 v120, 0xffffffba, v179
	v_cndmask_b32_e64 v123, v124, 0, s[4:5]
	v_sub_u32_e32 v125, 0x46, v179
	v_cmp_gt_i32_e32 vcc, 0, v120
	v_mul_f32_e32 v123, v123, v126
	v_add_u32_e32 v124, 0xffffffb9, v179
	v_max_i32_e32 v125, v120, v125
	v_cndmask_b32_e32 v126, v173, v176, vcc
	v_cmp_lt_i32_e32 vcc, 0, v120
	v_sub_u32_e32 v120, 0x47, v179
	s_waitcnt lgkmcnt(3)
	v_mfma_f32_16x16x32_bf16 v[108:111], v[108:111], v[56:59], 0
	v_cndmask_b32_e32 v120, v120, v124, vcc
	v_cvt_f32_u32_e32 v120, v120
	v_cndmask_b32_e32 v124, v176, v173, vcc
	s_waitcnt lgkmcnt(1)
	v_mfma_f32_16x16x32_bf16 v[56:59], v[100:103], v[56:59], 0
	v_cvt_f32_u32_e32 v125, v125
	v_mul_f32_e64 v120, -v124, v120
	v_add_u32_e32 v124, 0x47, v178
	v_cmp_gt_i32_e32 vcc, s22, v124
	v_mfma_f32_16x16x32_bf16 v[104:107], v[104:107], v[52:55], v[108:111]
	s_and_b64 s[0:1], s[2:3], vcc
	v_mul_f32_e32 v120, 0x3fb8aa3b, v120
	v_exp_f32_e32 v120, v120
	s_waitcnt lgkmcnt(0)
	v_mfma_f32_16x16x32_bf16 v[52:55], v[96:99], v[52:55], v[56:59]
	v_mul_f32_e64 v125, -v126, v125
	v_mul_f32_e32 v125, 0x3fb8aa3b, v125
	v_exp_f32_e32 v125, v125
	v_add_u32_e32 v56, 0xffffffa0, v179
	v_sub_u32_e32 v58, 0x60, v179
	v_cmp_gt_i32_e32 vcc, 0, v56
	v_add_u32_e32 v57, 0xffffff9f, v179
	v_max_i32_e32 v58, v56, v58
	v_cndmask_b32_e32 v59, v173, v176, vcc
	v_cmp_lt_i32_e32 vcc, 0, v56
	v_sub_u32_e32 v56, 0x61, v179
	v_cvt_f32_u32_e32 v58, v58
	v_cndmask_b32_e32 v56, v56, v57, vcc
	v_cvt_f32_u32_e32 v56, v56
	v_cndmask_b32_e32 v57, v176, v173, vcc
	v_mul_f32_e64 v58, -v59, v58
	v_cndmask_b32_e64 v120, v120, 0, s[0:1]
	v_mul_f32_e64 v56, -v57, v56
	v_mul_f32_e32 v56, 0x3fb8aa3b, v56
	v_exp_f32_e32 v56, v56
	v_add_u32_e32 v57, 0x61, v178
	v_mul_f32_e32 v58, 0x3fb8aa3b, v58
	v_cmp_gt_i32_e64 s[0:1], s22, v57
	v_exp_f32_e32 v58, v58
	s_and_b64 s[0:1], s[2:3], s[0:1]
	v_cndmask_b32_e64 v56, v56, 0, s[0:1]
	v_cmp_gt_i32_e32 vcc, 2, v177
	v_mul_f32_e32 v52, v56, v52
	v_add_u32_e32 v56, 0xffffff9e, v179
	v_cndmask_b32_e64 v124, v125, 0, s[4:5]
	s_and_b64 s[4:5], s[2:3], vcc
	v_sub_u32_e32 v59, 0x62, v179
	v_cmp_gt_i32_e32 vcc, 0, v56
	v_cndmask_b32_e64 v57, v58, 0, s[4:5]
	v_add_u32_e32 v58, 0xffffff9d, v179
	v_max_i32_e32 v59, v56, v59
	v_cndmask_b32_e32 v96, v173, v176, vcc
	v_cmp_lt_i32_e32 vcc, 0, v56
	v_sub_u32_e32 v56, 0x63, v179
	v_cvt_f32_u32_e32 v59, v59
	v_cndmask_b32_e32 v56, v56, v58, vcc
	v_cvt_f32_u32_e32 v56, v56
	v_cndmask_b32_e32 v58, v176, v173, vcc
	v_mul_f32_e64 v59, -v96, v59
	v_mul_f32_e32 v59, 0x3fb8aa3b, v59
	v_mul_f32_e64 v56, -v58, v56
	v_mul_f32_e32 v56, 0x3fb8aa3b, v56
	v_exp_f32_e32 v56, v56
	v_add_u32_e32 v58, 0x63, v178
	v_cmp_gt_i32_e32 vcc, s22, v58
	v_exp_f32_e32 v59, v59
	s_and_b64 s[0:1], s[2:3], vcc
	v_cndmask_b32_e64 v56, v56, 0, s[0:1]
	v_mul_f32_e32 v53, v56, v53
	v_add_u32_e32 v56, 0xffffff9c, v179
	v_sub_u32_e32 v96, 0x64, v179
	v_cmp_gt_i32_e32 vcc, 0, v56
	v_cndmask_b32_e64 v58, v59, 0, s[4:5]
	v_add_u32_e32 v59, 0xffffff9b, v179
	v_max_i32_e32 v96, v56, v96
	v_cndmask_b32_e32 v97, v173, v176, vcc
	v_cmp_lt_i32_e32 vcc, 0, v56
	v_sub_u32_e32 v56, 0x65, v179
	v_cvt_f32_u32_e32 v96, v96
	v_cndmask_b32_e32 v56, v56, v59, vcc
	v_cvt_f32_u32_e32 v56, v56
	v_cndmask_b32_e32 v59, v176, v173, vcc
	v_mul_f32_e64 v96, -v97, v96
	v_mul_f32_e32 v96, 0x3fb8aa3b, v96
	v_mul_f32_e64 v56, -v59, v56
	v_mul_f32_e32 v56, 0x3fb8aa3b, v56
	v_exp_f32_e32 v56, v56
	v_add_u32_e32 v59, 0x65, v178
	v_cmp_gt_i32_e32 vcc, s22, v59
	v_exp_f32_e32 v96, v96
	s_and_b64 s[0:1], s[2:3], vcc
	v_cndmask_b32_e64 v56, v56, 0, s[0:1]
	v_mul_f32_e32 v54, v56, v54
	v_add_u32_e32 v56, 0xffffff9a, v179
	v_sub_u32_e32 v97, 0x66, v179
	v_cmp_gt_i32_e32 vcc, 0, v56
	v_cndmask_b32_e64 v59, v96, 0, s[4:5]
	v_add_u32_e32 v96, 0xffffff99, v179
	v_max_i32_e32 v97, v56, v97
	v_cndmask_b32_e32 v98, v173, v176, vcc
	v_cmp_lt_i32_e32 vcc, 0, v56
	v_sub_u32_e32 v56, 0x67, v179
	v_cvt_f32_u32_e32 v97, v97
	v_cndmask_b32_e32 v56, v56, v96, vcc
	v_cvt_f32_u32_e32 v56, v56
	v_cndmask_b32_e32 v96, v176, v173, vcc
	v_mul_f32_e64 v97, -v98, v97
	v_mul_f32_e32 v97, 0x3fb8aa3b, v97
	v_mul_f32_e64 v56, -v96, v56
	v_mul_f32_e32 v56, 0x3fb8aa3b, v56
	v_exp_f32_e32 v97, v97
	v_exp_f32_e32 v56, v56
	v_add_u32_e32 v96, 0x67, v178
	v_cmp_gt_i32_e32 vcc, s22, v96
	s_and_b64 s[0:1], s[2:3], vcc
	v_cndmask_b32_e64 v96, v97, 0, s[4:5]
	v_cndmask_b32_e64 v56, v56, 0, s[0:1]
	v_mul_f32_e32 v95, v168, v95
	v_mul_f32_e32 v147, v169, v147
	v_mul_f32_e32 v136, v136, v139
	v_mul_f32_e32 v115, v132, v115
	v_mul_f32_e32 v124, v124, v127
	v_mul_f32_e32 v119, v120, v119
	v_mul_f32_e32 v57, v57, v104
	v_mul_f32_e32 v58, v58, v105
	v_mul_f32_e32 v59, v59, v106
	v_mul_f32_e32 v96, v96, v107
	v_mul_f32_e32 v55, v56, v55
	v_mul_u32_u24_e32 v56, 0x120, v175
	v_readlane_b32 s0, v254, 59
	v_cvt_pk_bf16_f32 v92, v92, v144
	v_cvt_pk_bf16_f32 v93, v93, v145
	v_cvt_pk_bf16_f32 v94, v94, v146
	v_cvt_pk_bf16_f32 v95, v95, v147
	v_cvt_pk_bf16_f32 v112, v133, v112
	v_cvt_pk_bf16_f32 v113, v134, v113
	v_cvt_pk_bf16_f32 v114, v135, v114
	v_cvt_pk_bf16_f32 v115, v136, v115
	v_cvt_pk_bf16_f32 v116, v121, v116
	v_cvt_pk_bf16_f32 v117, v122, v117
	v_cvt_pk_bf16_f32 v118, v123, v118
	v_cvt_pk_bf16_f32 v119, v124, v119
	v_cvt_pk_bf16_f32 v52, v57, v52
	v_cvt_pk_bf16_f32 v53, v58, v53
	v_cvt_pk_bf16_f32 v54, v59, v54
	v_cvt_pk_bf16_f32 v55, v96, v55
	v_add3_u32 v155, s0, v56, v155
	ds_read_b128 v[56:59], v155
	ds_read_b128 v[96:99], v155 offset:64
	ds_read_b128 v[100:103], v155 offset:4608
	ds_read_b128 v[104:107], v155 offset:4672
	ds_read_b128 v[108:111], v155 offset:9216
	ds_read_b128 v[120:123], v155 offset:9280
	ds_read_b128 v[124:127], v155 offset:13824
	ds_read_b128 v[128:131], v155 offset:13888
	ds_read_b128 v[132:135], v155 offset:18432
	ds_read_b128 v[136:139], v155 offset:18496
	ds_read_b128 v[140:143], v155 offset:23040
	ds_read_b128 v[144:147], v155 offset:23104
	ds_read_b128 v[176:179], v155 offset:27648
	ds_read_b128 v[180:183], v155 offset:27712
	ds_read_b128 v[184:187], v155 offset:32256
	ds_read_b128 v[188:191], v155 offset:32320
	s_waitcnt lgkmcnt(14)
	v_mfma_f32_16x16x32_bf16 v[56:59], v[56:59], v[92:95], v[60:63]
	s_waitcnt lgkmcnt(13)
	v_mfma_f32_16x16x32_bf16 v[60:63], v[100:103], v[92:95], v[64:67]
	s_waitcnt lgkmcnt(11)
	v_mfma_f32_16x16x32_bf16 v[64:67], v[108:111], v[92:95], v[68:71]
	s_waitcnt lgkmcnt(9)
	v_mfma_f32_16x16x32_bf16 v[68:71], v[124:127], v[92:95], v[72:75]
	s_waitcnt lgkmcnt(7)
	v_mfma_f32_16x16x32_bf16 v[72:75], v[132:135], v[92:95], v[76:79]
	s_waitcnt lgkmcnt(5)
	v_mfma_f32_16x16x32_bf16 v[76:79], v[140:143], v[92:95], v[80:83]
	s_waitcnt lgkmcnt(3)
	v_mfma_f32_16x16x32_bf16 v[80:83], v[176:179], v[92:95], v[84:87]
	s_waitcnt lgkmcnt(1)
	v_mfma_f32_16x16x32_bf16 v[84:87], v[184:187], v[92:95], v[88:91]
	v_mfma_f32_16x16x32_bf16 v[56:59], v[96:99], v[112:115], v[56:59]
	v_mfma_f32_16x16x32_bf16 v[60:63], v[104:107], v[112:115], v[60:63]
	v_mfma_f32_16x16x32_bf16 v[64:67], v[120:123], v[112:115], v[64:67]
	v_mfma_f32_16x16x32_bf16 v[68:71], v[128:131], v[112:115], v[68:71]
	v_mfma_f32_16x16x32_bf16 v[72:75], v[136:139], v[112:115], v[72:75]
	v_mfma_f32_16x16x32_bf16 v[76:79], v[144:147], v[112:115], v[76:79]
	v_mfma_f32_16x16x32_bf16 v[80:83], v[180:183], v[112:115], v[80:83]
	s_waitcnt lgkmcnt(0)
	v_mfma_f32_16x16x32_bf16 v[84:87], v[188:191], v[112:115], v[84:87]
	ds_read_b128 v[88:91], v155 offset:128
	ds_read_b128 v[92:95], v155 offset:192
	ds_read_b128 v[96:99], v155 offset:4736
	ds_read_b128 v[100:103], v155 offset:4800
	ds_read_b128 v[104:107], v155 offset:9344
	ds_read_b128 v[108:111], v155 offset:9408
	ds_read_b128 v[112:115], v155 offset:13952
	ds_read_b128 v[120:123], v155 offset:14016
	ds_read_b128 v[124:127], v155 offset:18560
	ds_read_b128 v[128:131], v155 offset:18624
	ds_read_b128 v[132:135], v155 offset:23168
	ds_read_b128 v[136:139], v155 offset:23232
	ds_read_b128 v[140:143], v155 offset:27776
	ds_read_b128 v[144:147], v155 offset:27840
	ds_read_b128 v[176:179], v155 offset:32384
	ds_read_b128 v[180:183], v155 offset:32448
	s_waitcnt lgkmcnt(14)
	v_mfma_f32_16x16x32_bf16 v[56:59], v[88:91], v[116:119], v[56:59]
	s_waitcnt lgkmcnt(13)
	v_mfma_f32_16x16x32_bf16 v[60:63], v[96:99], v[116:119], v[60:63]
	s_waitcnt lgkmcnt(11)
	v_mfma_f32_16x16x32_bf16 v[64:67], v[104:107], v[116:119], v[64:67]
	s_waitcnt lgkmcnt(9)
	v_mfma_f32_16x16x32_bf16 v[68:71], v[112:115], v[116:119], v[68:71]
	s_waitcnt lgkmcnt(7)
	v_mfma_f32_16x16x32_bf16 v[88:91], v[124:127], v[116:119], v[72:75]
	s_waitcnt lgkmcnt(5)
	v_mfma_f32_16x16x32_bf16 v[96:99], v[132:135], v[116:119], v[76:79]
	s_waitcnt lgkmcnt(3)
	v_mfma_f32_16x16x32_bf16 v[104:107], v[140:143], v[116:119], v[80:83]
	s_waitcnt lgkmcnt(1)
	v_mfma_f32_16x16x32_bf16 v[84:87], v[176:179], v[116:119], v[84:87]
	v_mfma_f32_16x16x32_bf16 v[80:83], v[92:95], v[52:55], v[56:59]
	v_mfma_f32_16x16x32_bf16 v[76:79], v[100:103], v[52:55], v[60:63]
	v_mfma_f32_16x16x32_bf16 v[72:75], v[108:111], v[52:55], v[64:67]
	v_mfma_f32_16x16x32_bf16 v[68:71], v[120:123], v[52:55], v[68:71]
	v_mfma_f32_16x16x32_bf16 v[64:67], v[128:131], v[52:55], v[88:91]
	v_mfma_f32_16x16x32_bf16 v[60:63], v[136:139], v[52:55], v[96:99]
	v_mfma_f32_16x16x32_bf16 v[56:59], v[144:147], v[52:55], v[104:107]
	s_waitcnt lgkmcnt(0)
	v_mfma_f32_16x16x32_bf16 v[52:55], v[180:183], v[52:55], v[84:87]
	s_nop 2
	v_mov_b32_e32 v84, v80
	v_mov_b32_e32 v85, v76
	v_mov_b32_e32 v86, v81
	v_mov_b32_e32 v87, v77
	v_pk_add_f32 v[84:85], v[84:85], v[86:87]
	v_mov_b32_e32 v86, v82
	v_mov_b32_e32 v87, v78
	v_mov_b32_e32 v88, v83
	v_mov_b32_e32 v89, v79
	v_pk_add_f32 v[86:87], v[86:87], v[88:89]
	v_mov_b32_e32 v88, v72
	v_pk_add_f32 v[84:85], v[84:85], v[86:87]
	v_mov_b32_e32 v86, v73
	v_mov_b32_e32 v87, v74
	v_mov_b32_e32 v89, v75
	v_pk_add_f32 v[86:87], v[86:87], v[88:89]
	v_add_f32_e32 v84, 0, v84
	v_pk_add_f32 v[86:87], v[86:87], v[86:87] op_sel:[0,1] op_sel_hi:[1,0]
	v_add_f32_e32 v84, v84, v85
	v_add_f32_e32 v88, v68, v69
	v_add_f32_e32 v90, v70, v71
	v_mov_b32_e32 v85, v64
	v_mov_b32_e32 v87, v65
	v_mov_b32_e32 v89, v66
	v_mov_b32_e32 v91, v67
	v_pk_add_f32 v[84:85], v[84:85], v[86:87]
	v_pk_add_f32 v[86:87], v[88:89], v[90:91]
	v_mov_b32_e32 v88, v60
	v_pk_add_f32 v[84:85], v[84:85], v[86:87]
	v_mov_b32_e32 v86, v61
	v_mov_b32_e32 v87, v62
	v_mov_b32_e32 v89, v63
	v_pk_add_f32 v[86:87], v[86:87], v[88:89]
	v_pk_add_f32 v[84:85], v[84:85], v[84:85] op_sel:[0,1] op_sel_hi:[1,0]
	v_pk_add_f32 v[86:87], v[86:87], v[86:87] op_sel:[0,1] op_sel_hi:[1,0]
	v_add_f32_e32 v88, v56, v57
	v_add_f32_e32 v90, v58, v59
	v_mov_b32_e32 v85, v52
	v_mov_b32_e32 v87, v53
	v_mov_b32_e32 v89, v54
	v_mov_b32_e32 v91, v55
	v_pk_add_f32 v[84:85], v[84:85], v[86:87]
	v_pk_add_f32 v[86:87], v[88:89], v[90:91]
	v_and_b32_e32 v2, 16, v2
	v_pk_add_f32 v[84:85], v[84:85], v[86:87]
	v_and_b32_e32 v86, 64, v217
	v_add_f32_e32 v84, v84, v85
	v_xor_b32_e32 v85, 16, v217
	v_add_u32_e32 v86, 64, v86
	v_cmp_lt_i32_e32 vcc, v85, v86
	v_lshlrev_b32_e32 v2, 1, v2
	s_nop 0
	v_cndmask_b32_e32 v85, v217, v85, vcc
	v_lshlrev_b32_e32 v94, 2, v85
	ds_bpermute_b32 v85, v94, v84
	s_waitcnt lgkmcnt(0)
	v_add_f32_e32 v84, v84, v85
	v_xor_b32_e32 v85, 32, v217
	v_cmp_lt_i32_e32 vcc, v85, v86
	s_nop 1
	v_cndmask_b32_e32 v85, v217, v85, vcc
	v_lshlrev_b32_e32 v95, 2, v85
	ds_bpermute_b32 v85, v95, v84
	s_waitcnt lgkmcnt(0)
	v_add_f32_e32 v96, v84, v85
	v_fmamk_f32 v81, v96, 0xbc000000, v81
	v_fmamk_f32 v77, v96, 0xbc000000, v77
	v_fmamk_f32 v83, v96, 0xbc000000, v83
	v_fmac_f32_e32 v80, 0xbc000000, v96
	v_fmamk_f32 v79, v96, 0xbc000000, v79
	v_fmac_f32_e32 v76, 0xbc000000, v96
	v_mov_b32_e32 v86, v81
	v_mov_b32_e32 v87, v77
	v_fmamk_f32 v82, v96, 0xbc000000, v82
	v_fmamk_f32 v78, v96, 0xbc000000, v78
	v_mov_b32_e32 v84, v80
	v_mov_b32_e32 v85, v76
	v_pk_mul_f32 v[86:87], v[86:87], v[86:87]
	v_mov_b32_e32 v88, v83
	v_mov_b32_e32 v89, v79
	v_pk_fma_f32 v[84:85], v[84:85], v[84:85], v[86:87]
	v_mov_b32_e32 v86, v82
	v_mov_b32_e32 v87, v78
	v_pk_mul_f32 v[88:89], v[88:89], v[88:89]
	v_fmamk_f32 v73, v96, 0xbc000000, v73
	v_pk_fma_f32 v[86:87], v[86:87], v[86:87], v[88:89]
	v_fmamk_f32 v72, v96, 0xbc000000, v72
	v_pk_add_f32 v[84:85], v[84:85], v[86:87]
	v_fmamk_f32 v75, v96, 0xbc000000, v75
	v_fmac_f32_e32 v74, 0xbc000000, v96
	v_pk_add_f32 v[84:85], v[84:85], v[84:85] op_sel_hi:[0,1]
	v_pk_mul_f32 v[86:87], v[74:75], v[74:75]
	v_pk_mul_f32 v[88:89], v[72:73], v[72:73]
	v_fmamk_f32 v68, v96, 0xbc000000, v68
	v_pk_mov_b32 v[90:91], v[88:89], v[86:87] op_sel:[1,0]
	v_mov_b32_e32 v89, v87
	v_fmamk_f32 v69, v96, 0xbc000000, v69
	v_fmac_f32_e32 v70, 0xbc000000, v96
	v_mul_f32_e32 v84, v68, v68
	v_pk_add_f32 v[86:87], v[90:91], v[88:89]
	v_fmamk_f32 v71, v96, 0xbc000000, v71
	v_pk_fma_f32 v[88:89], v[68:69], v[68:69], v[84:85] op_sel_hi:[1,1,0]
	v_mul_f32_e32 v84, v70, v70
	v_pk_add_f32 v[86:87], v[86:87], v[86:87] op_sel_hi:[0,1]
	v_pk_fma_f32 v[90:91], v[70:71], v[70:71], v[84:85] op_sel_hi:[1,1,0]
	v_fmamk_f32 v67, v96, 0xbc000000, v67
	v_fmamk_f32 v66, v96, 0xbc000000, v66
	v_fmamk_f32 v65, v96, 0xbc000000, v65
	v_fmac_f32_e32 v64, 0xbc000000, v96
	v_mul_f32_e32 v88, v64, v64
	v_mul_f32_e32 v90, v65, v65
	v_mul_f32_e32 v86, v66, v66
	v_mul_f32_e32 v84, v67, v67
	v_pk_add_f32 v[88:89], v[88:89], v[90:91]
	v_pk_add_f32 v[84:85], v[86:87], v[84:85]
	v_fmamk_f32 v61, v96, 0xbc000000, v61
	v_fmamk_f32 v60, v96, 0xbc000000, v60
	v_fmamk_f32 v63, v96, 0xbc000000, v63
	v_fmac_f32_e32 v62, 0xbc000000, v96
	v_pk_add_f32 v[84:85], v[88:89], v[84:85]
	v_pk_mul_f32 v[86:87], v[62:63], v[62:63]
	v_pk_mul_f32 v[88:89], v[60:61], v[60:61]
	v_fmac_f32_e32 v58, 0xbc000000, v96
	v_pk_mov_b32 v[90:91], v[88:89], v[86:87] op_sel:[1,0]
	v_mov_b32_e32 v89, v87
	v_pk_add_f32 v[86:87], v[90:91], v[88:89]
	v_fmamk_f32 v88, v96, 0xbc000000, v56
	v_fmamk_f32 v89, v96, 0xbc000000, v57
	v_mul_f32_e32 v56, v88, v88
	v_pk_fma_f32 v[56:57], v[88:89], v[88:89], v[56:57] op_sel_hi:[1,1,0]
	v_fmamk_f32 v59, v96, 0xbc000000, v59
	v_mul_f32_e32 v56, v58, v58
	v_pk_add_f32 v[84:85], v[84:85], v[84:85] op_sel_hi:[0,1]
	v_pk_add_f32 v[86:87], v[86:87], v[86:87] op_sel_hi:[0,1]
	v_pk_fma_f32 v[90:91], v[58:59], v[58:59], v[56:57] op_sel_hi:[1,1,0]
	v_fmamk_f32 v93, v96, 0xbc000000, v55
	v_fmamk_f32 v92, v96, 0xbc000000, v54
	v_fmamk_f32 v53, v96, 0xbc000000, v53
	v_fmac_f32_e32 v52, 0xbc000000, v96
	v_mul_f32_e32 v56, v52, v52
	v_mul_f32_e32 v90, v53, v53
	v_mul_f32_e32 v86, v92, v92
	v_mul_f32_e32 v84, v93, v93
	v_pk_add_f32 v[54:55], v[56:57], v[90:91]
	v_pk_add_f32 v[56:57], v[86:87], v[84:85]
	v_mov_b64_e32 v[96:97], s[96:97]
	v_pk_add_f32 v[54:55], v[54:55], v[56:57]
	s_waitcnt vmcnt(7)
	v_lshlrev_b32_e32 v56, 16, v163
	v_add_f32_e32 v54, v54, v55
	ds_bpermute_b32 v55, v94, v54
	v_and_b32_e32 v57, 0xffff0000, v163
	s_waitcnt vmcnt(6)
	v_lshlrev_b32_e32 v90, 16, v160
	v_and_b32_e32 v91, 0xffff0000, v160
	v_lshlrev_b32_e32 v94, 16, v161
	s_waitcnt lgkmcnt(0)
	v_add_f32_e32 v54, v54, v55
	ds_bpermute_b32 v55, v95, v54
	v_and_b32_e32 v95, 0xffff0000, v161
	v_mad_i64_i32 v[96:97], s[0:1], v154, s48, v[96:97]
	v_and_b32_e32 v86, -8, v172
	s_waitcnt lgkmcnt(0)
	v_add_f32_e32 v54, v54, v55
	v_fmamk_f32 v54, v54, 0x3c000000, v219
	v_mul_f32_e32 v55, 0x4b800000, v54
	v_cmp_gt_f32_e32 vcc, s35, v54
	v_lshl_add_u64 v[96:97], v[96:97], 0, s[18:19]
	v_ashrrev_i32_e32 v87, 31, v86
	v_cndmask_b32_e32 v54, v54, v55, vcc
	v_rsq_f32_e32 v54, v54
	s_nop 0
	v_mul_f32_e32 v55, 0x45800000, v54
	v_cndmask_b32_e32 v84, v54, v55, vcc
	v_lshlrev_b32_e32 v54, 16, v162
	v_and_b32_e32 v55, 0xffff0000, v162
	v_pk_mul_f32 v[80:81], v[80:81], v[84:85] op_sel_hi:[1,0]
	v_pk_mul_f32 v[82:83], v[82:83], v[84:85] op_sel_hi:[1,0]
	v_pk_mul_f32 v[76:77], v[76:77], v[84:85] op_sel_hi:[1,0]
	v_pk_mul_f32 v[78:79], v[78:79], v[84:85] op_sel_hi:[1,0]
	v_pk_mul_f32 v[56:57], v[82:83], v[56:57]
	v_pk_mul_f32 v[54:55], v[80:81], v[54:55]
	v_pk_mul_f32 v[78:79], v[78:79], v[94:95]
	v_pk_mul_f32 v[76:77], v[76:77], v[90:91]
	v_cvt_pk_bf16_f32 v54, v54, v55
	v_cvt_pk_bf16_f32 v55, v56, v57
	v_cvt_pk_bf16_f32 v56, v76, v77
	v_cvt_pk_bf16_f32 v57, v78, v79
	v_lshl_add_u64 v[76:77], v[96:97], 0, v[2:3]
	v_permlane16_swap_b32_e32 v54, v56
	v_permlane16_swap_b32_e32 v55, v57
	v_lshl_add_u64 v[76:77], v[86:87], 1, v[76:77]
	global_store_dwordx4 v[76:77], v[54:57], off
	s_waitcnt vmcnt(5)
	v_lshlrev_b32_e32 v78, 16, v156
	v_and_b32_e32 v79, 0xffff0000, v156
	v_lshlrev_b32_e32 v54, 16, v158
	v_and_b32_e32 v55, 0xffff0000, v158
	v_lshlrev_b32_e32 v56, 16, v159
	v_and_b32_e32 v57, 0xffff0000, v159
	v_lshlrev_b32_e32 v80, 16, v157
	v_and_b32_e32 v81, 0xffff0000, v157
	v_pk_mul_f32 v[72:73], v[72:73], v[84:85] op_sel_hi:[1,0]
	v_pk_mul_f32 v[74:75], v[74:75], v[84:85] op_sel_hi:[1,0]
	v_pk_mul_f32 v[68:69], v[68:69], v[84:85] op_sel_hi:[1,0]
	v_pk_mul_f32 v[70:71], v[70:71], v[84:85] op_sel_hi:[1,0]
	v_pk_mul_f32 v[56:57], v[74:75], v[56:57]
	v_pk_mul_f32 v[54:55], v[72:73], v[54:55]
	v_pk_mul_f32 v[70:71], v[70:71], v[80:81]
	v_pk_mul_f32 v[68:69], v[68:69], v[78:79]
	v_cvt_pk_bf16_f32 v54, v54, v55
	v_cvt_pk_bf16_f32 v55, v56, v57
	v_cvt_pk_bf16_f32 v56, v68, v69
	v_cvt_pk_bf16_f32 v57, v70, v71
	s_nop 0
	v_permlane16_swap_b32_e32 v54, v56
	v_permlane16_swap_b32_e32 v55, v57
	global_store_dwordx4 v[76:77], v[54:57], off offset:64
	s_waitcnt vmcnt(4)
	v_lshlrev_b32_e32 v68, 16, v150
	v_and_b32_e32 v69, 0xffff0000, v150
	v_lshlrev_b32_e32 v54, 16, v152
	v_and_b32_e32 v55, 0xffff0000, v152
	v_lshlrev_b32_e32 v56, 16, v153
	v_and_b32_e32 v57, 0xffff0000, v153
	v_lshlrev_b32_e32 v70, 16, v151
	v_and_b32_e32 v71, 0xffff0000, v151
	v_pk_mul_f32 v[64:65], v[64:65], v[84:85] op_sel_hi:[1,0]
	v_pk_mul_f32 v[66:67], v[66:67], v[84:85] op_sel_hi:[1,0]
	v_pk_mul_f32 v[60:61], v[60:61], v[84:85] op_sel_hi:[1,0]
	v_pk_mul_f32 v[62:63], v[62:63], v[84:85] op_sel_hi:[1,0]
	v_pk_mul_f32 v[56:57], v[66:67], v[56:57]
	v_pk_mul_f32 v[54:55], v[64:65], v[54:55]
	v_pk_mul_f32 v[62:63], v[62:63], v[70:71]
	v_pk_mul_f32 v[60:61], v[60:61], v[68:69]
	v_cvt_pk_bf16_f32 v54, v54, v55
	v_cvt_pk_bf16_f32 v55, v56, v57
	v_cvt_pk_bf16_f32 v56, v60, v61
	v_cvt_pk_bf16_f32 v57, v62, v63
	s_nop 0
	v_permlane16_swap_b32_e32 v54, v56
	v_permlane16_swap_b32_e32 v55, v57
	global_store_dwordx4 v[76:77], v[54:57], off offset:128
	v_pk_mul_f32 v[58:59], v[58:59], v[84:85] op_sel_hi:[1,0]
	s_waitcnt vmcnt(3)
	v_lshlrev_b32_e32 v60, 16, v0
	v_lshlrev_b32_e32 v56, 16, v149
	v_and_b32_e32 v57, 0xffff0000, v149
	v_lshlrev_b32_e32 v54, 16, v148
	v_and_b32_e32 v55, 0xffff0000, v148
	v_and_b32_e32 v61, 0xffff0000, v0
	v_lshlrev_b32_e32 v0, 16, v1
	v_and_b32_e32 v1, 0xffff0000, v1
	v_pk_mul_f32 v[62:63], v[88:89], v[84:85] op_sel_hi:[1,0]
	v_pk_mul_f32 v[56:57], v[58:59], v[56:57]
	v_pk_mul_f32 v[52:53], v[52:53], v[84:85] op_sel_hi:[1,0]
	v_pk_mul_f32 v[58:59], v[92:93], v[84:85] op_sel_hi:[1,0]
	v_pk_mul_f32 v[54:55], v[62:63], v[54:55]
	v_pk_mul_f32 v[0:1], v[58:59], v[0:1]
	v_pk_mul_f32 v[58:59], v[52:53], v[60:61]
	v_cvt_pk_bf16_f32 v52, v54, v55
	v_cvt_pk_bf16_f32 v53, v56, v57
	v_cvt_pk_bf16_f32 v54, v58, v59
	v_cvt_pk_bf16_f32 v55, v0, v1
	s_nop 0
	v_permlane16_swap_b32_e32 v52, v54
	v_permlane16_swap_b32_e32 v53, v55
	global_store_dwordx4 v[76:77], v[52:55], off offset:192
	v_readlane_b32 s0, v254, 18
	s_waitcnt vmcnt(4)
	s_branch .Lret_join

.Lret_join:
	v_mov_b64_e32 v[54:55], v[50:51]
	v_mov_b64_e32 v[58:59], v[46:47]
	s_add_i32 s20, s20, s0
	s_andn2_b64 vcc, exec, s[40:41]
	s_mov_b32 s4, s21
	v_mov_b64_e32 v[52:53], v[48:49]
	v_mov_b64_e32 v[56:57], v[44:45]
	s_cbranch_vccz .LBB0_564

.LBB0_936:
	v_mov_b32_e32 v122, v27
	v_mov_b32_e32 v123, v113
	v_mov_b32_e32 v124, v108
	v_mov_b32_e32 v125, v108
	v_mov_b32_e32 v109, v108
	v_lshlrev_b32_e32 v114, 16, v24
	v_and_b32_e32 v115, 0xffff0000, v24
	v_lshlrev_b32_e32 v24, 16, v25
	v_and_b32_e32 v25, 0xffff0000, v25
	v_pk_mul_f32 v[122:123], v[124:125], v[122:123]
	v_mov_b32_e32 v27, v112
	v_pk_mul_f32 v[112:113], v[108:109], v[26:27]
	s_waitcnt vmcnt(3)
	v_pk_fma_f32 v[26:27], v[14:15], v[122:123], v[24:25]
	v_cndmask_b32_e64 v24, 0, 1, s[12:13]
	v_cmp_ne_u32_e64 s[46:47], 1, v24
	s_andn2_b64 vcc, exec, s[12:13]
	v_pk_fma_f32 v[24:25], v[12:13], v[112:113], v[114:115]
	s_cbranch_vccnz .LBB0_991
	v_cvt_pk_bf16_f32 v112, v24, v25
	v_cvt_pk_bf16_f32 v113, v26, v27
	global_store_dwordx2 v[102:103], v[112:113], off offset:512
	s_cbranch_execnz .LBB0_939

.LBB0_939:
	v_pk_mul_f32 v[114:115], v[108:109], v[30:31]
	v_mov_b32_e32 v30, v108
	v_mov_b32_e32 v31, v108
	v_lshlrev_b32_e32 v112, 16, v28
	v_and_b32_e32 v113, 0xffff0000, v28
	v_lshlrev_b32_e32 v28, 16, v29
	v_and_b32_e32 v29, 0xffff0000, v29
	v_pk_mul_f32 v[30:31], v[30:31], v[106:107]
	s_and_b64 vcc, exec, s[46:47]
	s_waitcnt vmcnt(3)
	v_pk_fma_f32 v[30:31], v[10:11], v[30:31], v[28:29]
	v_pk_fma_f32 v[28:29], v[8:9], v[114:115], v[112:113]
	s_cbranch_vccnz .LBB0_992
	v_cvt_pk_bf16_f32 v106, v28, v29
	v_cvt_pk_bf16_f32 v107, v30, v31
	global_store_dwordx2 v[102:103], v[106:107], off offset:1024
	s_cbranch_execnz .LBB0_942

.LBB0_942:
	v_mov_b32_e32 v112, v108
	v_mov_b32_e32 v113, v108
	v_lshlrev_b32_e32 v106, 16, v32
	v_and_b32_e32 v107, 0xffff0000, v32
	v_lshlrev_b32_e32 v32, 16, v33
	v_and_b32_e32 v33, 0xffff0000, v33
	v_pk_mul_f32 v[104:105], v[104:105], v[112:113]
	v_pk_mul_f32 v[108:109], v[34:35], v[108:109]
	s_waitcnt vmcnt(3)
	v_pk_fma_f32 v[34:35], v[6:7], v[104:105], v[32:33]
	s_and_b64 vcc, exec, s[46:47]
	v_pk_fma_f32 v[32:33], v[4:5], v[108:109], v[106:107]
	s_cbranch_vccnz .LBB0_993
	v_cvt_pk_bf16_f32 v104, v32, v33
	v_cvt_pk_bf16_f32 v105, v34, v35
	global_store_dwordx2 v[102:103], v[104:105], off offset:1536
	s_cbranch_execnz .LBB0_945

.LBB0_1271:
	v_mov_b32_e32 v122, v27
	v_mov_b32_e32 v123, v113
	v_mov_b32_e32 v124, v108
	v_mov_b32_e32 v125, v108
	v_mov_b32_e32 v109, v108
	v_lshlrev_b32_e32 v114, 16, v24
	v_and_b32_e32 v115, 0xffff0000, v24
	v_lshlrev_b32_e32 v24, 16, v25
	v_and_b32_e32 v25, 0xffff0000, v25
	v_pk_mul_f32 v[122:123], v[124:125], v[122:123]
	v_mov_b32_e32 v27, v112
	v_pk_mul_f32 v[112:113], v[108:109], v[26:27]
	s_waitcnt vmcnt(3)
	v_pk_fma_f32 v[26:27], v[14:15], v[122:123], v[24:25]
	v_cndmask_b32_e64 v24, 0, 1, s[6:7]
	v_cmp_ne_u32_e64 s[40:41], 1, v24
	s_andn2_b64 vcc, exec, s[6:7]
	v_pk_fma_f32 v[24:25], v[12:13], v[112:113], v[114:115]
	s_cbranch_vccnz .LBB0_1326
	v_cvt_pk_bf16_f32 v112, v24, v25
	v_cvt_pk_bf16_f32 v113, v26, v27
	global_store_dwordx2 v[102:103], v[112:113], off offset:512
	s_cbranch_execnz .LBB0_1274

.LBB0_1274:
	v_pk_mul_f32 v[114:115], v[108:109], v[30:31]
	v_mov_b32_e32 v30, v108
	v_mov_b32_e32 v31, v108
	v_lshlrev_b32_e32 v112, 16, v28
	v_and_b32_e32 v113, 0xffff0000, v28
	v_lshlrev_b32_e32 v28, 16, v29
	v_and_b32_e32 v29, 0xffff0000, v29
	v_pk_mul_f32 v[30:31], v[30:31], v[106:107]
	s_and_b64 vcc, exec, s[40:41]
	s_waitcnt vmcnt(3)
	v_pk_fma_f32 v[30:31], v[10:11], v[30:31], v[28:29]
	v_pk_fma_f32 v[28:29], v[8:9], v[114:115], v[112:113]
	s_cbranch_vccnz .LBB0_1327
	v_cvt_pk_bf16_f32 v106, v28, v29
	v_cvt_pk_bf16_f32 v107, v30, v31
	global_store_dwordx2 v[102:103], v[106:107], off offset:1024
	s_cbranch_execnz .LBB0_1277

.LBB0_1277:
	v_mov_b32_e32 v112, v108
	v_mov_b32_e32 v113, v108
	v_lshlrev_b32_e32 v106, 16, v32
	v_and_b32_e32 v107, 0xffff0000, v32
	v_lshlrev_b32_e32 v32, 16, v33
	v_and_b32_e32 v33, 0xffff0000, v33
	v_pk_mul_f32 v[104:105], v[104:105], v[112:113]
	v_pk_mul_f32 v[108:109], v[34:35], v[108:109]
	s_waitcnt vmcnt(3)
	v_pk_fma_f32 v[34:35], v[6:7], v[104:105], v[32:33]
	s_and_b64 vcc, exec, s[40:41]
	v_pk_fma_f32 v[32:33], v[4:5], v[108:109], v[106:107]
	s_cbranch_vccnz .LBB0_1328
	v_cvt_pk_bf16_f32 v104, v32, v33
	v_cvt_pk_bf16_f32 v105, v34, v35
	global_store_dwordx2 v[102:103], v[104:105], off offset:1536
	s_cbranch_execnz .LBB0_1280
